# mixers w_out transpose items: 16 row loads issued back to back instead of one load + drain per iteration
# baseline (speedup 1.0000x reference)
.Lmc1_1:
	v_mov_b32_e32 v24, 0
	v_mov_b32_e32 v25, 0
	v_mov_b32_e32 v26, 0
	v_mov_b32_e32 v27, 0
	v_mov_b32_e32 v28, 0
	v_mov_b32_e32 v29, 0
	v_mov_b32_e32 v30, 0
	v_mov_b32_e32 v31, 0
	v_mov_b32_e32 v32, 0
	v_mov_b32_e32 v33, 0
	v_mov_b32_e32 v34, 0
	v_mov_b32_e32 v35, 0
	v_mov_b32_e32 v36, 0
	v_mov_b32_e32 v37, 0
	v_mov_b32_e32 v38, 0
	v_mov_b32_e32 v39, 0
	s_mov_b64 s[98:99], 0x4000
	s_mov_b64 s[10:11], exec
	s_and_saveexec_b64 s[4:5], s[0:1]
	v_add_u32_e32 v8, s12, v6
	v_ashrrev_i32_e32 v9, 31, v8
	v_lshlrev_b64 v[8:9], 12, v[8:9]
	v_lshl_add_u64 v[8:9], v[4:5], 0, v[8:9]
	global_load_dword v24, v[8:9], off
	v_lshl_add_u64 v[8:9], v[8:9], 0, s[98:99]
	global_load_dword v25, v[8:9], off
	v_lshl_add_u64 v[8:9], v[8:9], 0, s[98:99]
	global_load_dword v26, v[8:9], off
	v_lshl_add_u64 v[8:9], v[8:9], 0, s[98:99]
	global_load_dword v27, v[8:9], off
	v_lshl_add_u64 v[8:9], v[8:9], 0, s[98:99]
	global_load_dword v28, v[8:9], off
	v_lshl_add_u64 v[8:9], v[8:9], 0, s[98:99]
	global_load_dword v29, v[8:9], off
	v_lshl_add_u64 v[8:9], v[8:9], 0, s[98:99]
	global_load_dword v30, v[8:9], off
	v_lshl_add_u64 v[8:9], v[8:9], 0, s[98:99]
	global_load_dword v31, v[8:9], off
	v_lshl_add_u64 v[8:9], v[8:9], 0, s[98:99]
	global_load_dword v32, v[8:9], off
	v_lshl_add_u64 v[8:9], v[8:9], 0, s[98:99]
	global_load_dword v33, v[8:9], off
	v_lshl_add_u64 v[8:9], v[8:9], 0, s[98:99]
	global_load_dword v34, v[8:9], off
	v_lshl_add_u64 v[8:9], v[8:9], 0, s[98:99]
	global_load_dword v35, v[8:9], off
	v_lshl_add_u64 v[8:9], v[8:9], 0, s[98:99]
	global_load_dword v36, v[8:9], off
	v_lshl_add_u64 v[8:9], v[8:9], 0, s[98:99]
	global_load_dword v37, v[8:9], off
	v_lshl_add_u64 v[8:9], v[8:9], 0, s[98:99]
	global_load_dword v38, v[8:9], off
	v_lshl_add_u64 v[8:9], v[8:9], 0, s[98:99]
	global_load_dword v39, v[8:9], off
	s_or_b64 exec, exec, s[4:5]
	s_waitcnt vmcnt(0)
	ds_write_b32 v3, v24 offset:0
	ds_write_b32 v3, v25 offset:1040
	ds_write_b32 v3, v26 offset:2080
	ds_write_b32 v3, v27 offset:3120
	ds_write_b32 v3, v28 offset:4160
	ds_write_b32 v3, v29 offset:5200
	ds_write_b32 v3, v30 offset:6240
	ds_write_b32 v3, v31 offset:7280
	ds_write_b32 v3, v32 offset:8320
	ds_write_b32 v3, v33 offset:9360
	ds_write_b32 v3, v34 offset:10400
	ds_write_b32 v3, v35 offset:11440
	ds_write_b32 v3, v36 offset:12480
	ds_write_b32 v3, v37 offset:13520
	ds_write_b32 v3, v38 offset:14560
	ds_write_b32 v3, v39 offset:15600
	v_add_u32_e32 v3, 0x4100, v3
	v_add_u32_e32 v6, 64, v6
	v_mov_b32_e32 v7, v6
	s_branch .LBB0_841
